# loop-edge: loop-carried counter and address updates of both MLA tile loops moved from after the loop-back barrier to before it
# baseline (speedup 1.0000x reference)
; #define SBAR() __builtin_amdgcn_sched_barrier(0)
; __device__ __forceinline__ void finishSM(f32x16& p0, f32x16& p1, float alpha, float& l_reg, bf16x8& pa0, bf16x8& pa1, bf16x8& pa2, bf16x8& pa3) {
; #pragma unroll
;   for (int r = 0; r < 16; ++r) p1[r] = __builtin_amdgcn_exp2f(p1[r]);
;   float ps = 0;
; #pragma unroll
;   for (int r = 0; r < 16; ++r) ps += p0[r];
; #pragma unroll
;   for (int r = 0; r < 16; ++r) ps += p1[r];
;   { auto rr = __builtin_amdgcn_permlane32_swap(__float_as_uint(ps), __float_as_uint(ps), false, false);
;     ps = __uint_as_float(rr[0]) + __uint_as_float(rr[1]); }
;   l_reg = l_reg * alpha + ps;
;     ...
;   PK4(p0, 0, pa0); PK4(p0, 8, pa1); PK4(p1, 0, pa2); PK4(p1, 8, pa3);
; __device__ __forceinline__ void pv2(f32x16* o, int vb, bf16x8 pa0, bf16x8 pa1, bf16x8 pa2, bf16x8 pa3) {
;   VSet X, Y;
;   SBAR(); v_issue<0>(X, vb); v_issue<1>(Y, vb);
;   asm volatile("s_waitcnt lgkmcnt(8)" ::: "memory"); SBAR(); v_mma(o[0], X, pa0, pa1, pa2, pa3); SBAR();
;   v_issue<2>(X, vb);
.Lafter_b1:
	v_mul_f32_e32 v195, 0xbdd53b94, v220
	v_fmamk_f32 v80, v80, 0x3dd53b94, v195
	v_fmamk_f32 v81, v81, 0x3dd53b94, v195
	v_fmamk_f32 v82, v82, 0x3dd53b94, v195
	v_fmamk_f32 v83, v83, 0x3dd53b94, v195
	v_fmamk_f32 v84, v84, 0x3dd53b94, v195
	v_fmamk_f32 v85, v85, 0x3dd53b94, v195
	v_fmamk_f32 v86, v86, 0x3dd53b94, v195
	v_fmamk_f32 v87, v87, 0x3dd53b94, v195
	v_fmamk_f32 v88, v88, 0x3dd53b94, v195
	v_fmamk_f32 v89, v89, 0x3dd53b94, v195
	v_fmamk_f32 v90, v90, 0x3dd53b94, v195
	v_fmamk_f32 v91, v91, 0x3dd53b94, v195
	v_fmamk_f32 v92, v92, 0x3dd53b94, v195
	v_fmamk_f32 v93, v93, 0x3dd53b94, v195
	v_fmamk_f32 v94, v94, 0x3dd53b94, v195
	v_fmamk_f32 v95, v95, 0x3dd53b94, v195
	v_fmamk_f32 v64, v64, 0x3dd53b94, v195
	v_fmamk_f32 v65, v65, 0x3dd53b94, v195
	v_fmamk_f32 v66, v66, 0x3dd53b94, v195
	v_fmamk_f32 v67, v67, 0x3dd53b94, v195
	v_fmamk_f32 v68, v68, 0x3dd53b94, v195
	v_fmamk_f32 v69, v69, 0x3dd53b94, v195
	v_fmamk_f32 v70, v70, 0x3dd53b94, v195
	v_fmamk_f32 v71, v71, 0x3dd53b94, v195
	v_fmamk_f32 v72, v72, 0x3dd53b94, v195
	v_fmamk_f32 v73, v73, 0x3dd53b94, v195
	v_fmamk_f32 v74, v74, 0x3dd53b94, v195
	v_fmamk_f32 v75, v75, 0x3dd53b94, v195
	v_fmamk_f32 v76, v76, 0x3dd53b94, v195
	v_fmamk_f32 v77, v77, 0x3dd53b94, v195
	v_fmamk_f32 v78, v78, 0x3dd53b94, v195
	v_fmac_f32_e32 v195, 0x3dd53b94, v79
	v_exp_f32_e32 v79, v80
	v_exp_f32_e32 v80, v81
	v_exp_f32_e32 v81, v82
	v_exp_f32_e32 v82, v83
	v_exp_f32_e32 v83, v84
	v_exp_f32_e32 v196, v64
	v_add_f32_e32 v64, 0, v79
	v_exp_f32_e32 v84, v85
	v_add_f32_e32 v64, v80, v64
	v_exp_f32_e32 v85, v86
	v_add_f32_e32 v64, v81, v64
	v_exp_f32_e32 v86, v87
	v_add_f32_e32 v64, v82, v64
	v_exp_f32_e32 v87, v88
	v_add_f32_e32 v64, v83, v64
	v_exp_f32_e32 v88, v89
	v_add_f32_e32 v64, v84, v64
	v_exp_f32_e32 v89, v90
	v_add_f32_e32 v64, v85, v64
	v_exp_f32_e32 v90, v91
	v_add_f32_e32 v64, v86, v64
	v_exp_f32_e32 v91, v92
	v_add_f32_e32 v64, v87, v64
	v_exp_f32_e32 v92, v93
	v_add_f32_e32 v64, v88, v64
	v_exp_f32_e32 v93, v94
	v_add_f32_e32 v64, v89, v64
	v_exp_f32_e32 v94, v95
	v_add_f32_e32 v64, v90, v64
	v_add_f32_e32 v64, v91, v64
	v_add_f32_e32 v95, v222, v223
	v_exp_f32_e32 v197, v65
	v_add_f32_e32 v64, v92, v64
	v_fmac_f32_e32 v95, v214, v221
	v_exp_f32_e32 v221, v66
	v_add_f32_e32 v64, v93, v64
	v_exp_f32_e32 v222, v67
	v_add_f32_e32 v64, v94, v64
	v_exp_f32_e32 v223, v68
	v_add_f32_e32 v64, v196, v64
	v_exp_f32_e32 v224, v69
	v_add_f32_e32 v64, v197, v64
	v_exp_f32_e32 v225, v70
	v_add_f32_e32 v64, v221, v64
	v_exp_f32_e32 v226, v71
	v_add_f32_e32 v64, v222, v64
	v_exp_f32_e32 v227, v72
	v_add_f32_e32 v64, v223, v64
	v_exp_f32_e32 v228, v73
	v_add_f32_e32 v64, v224, v64
	v_exp_f32_e32 v229, v74
	v_add_f32_e32 v64, v225, v64
	v_exp_f32_e32 v230, v75
	v_add_f32_e32 v64, v226, v64
	v_exp_f32_e32 v231, v76
	v_add_f32_e32 v64, v227, v64
	v_exp_f32_e32 v232, v77
	v_add_f32_e32 v64, v228, v64
	v_exp_f32_e32 v233, v78
	v_add_f32_e32 v64, v229, v64
	v_exp_f32_e32 v195, v195
	v_add_f32_e32 v64, v230, v64
	v_add_f32_e32 v64, v231, v64
	v_add_f32_e32 v64, v232, v64
	v_add_f32_e32 v64, v233, v64
	v_add_f32_e32 v64, v195, v64
	v_mov_b32_e32 v65, v64
	s_nop 1
	v_permlane32_swap_b32_e32 v64, v65
	v_add_f32_e32 v214, v64, v65
	v_fmac_f32_e32 v214, v95, v194
	v_cvt_pk_bf16_f32 v64, v79, v80
	v_cvt_pk_bf16_f32 v65, v81, v82
	v_cvt_pk_bf16_f32 v66, v83, v84
	v_cvt_pk_bf16_f32 v67, v85, v86
	v_cvt_pk_bf16_f32 v68, v87, v88
	v_cvt_pk_bf16_f32 v69, v89, v90
	v_cvt_pk_bf16_f32 v70, v91, v92
	v_cvt_pk_bf16_f32 v71, v93, v94
	v_cvt_pk_bf16_f32 v72, v196, v197
	v_cvt_pk_bf16_f32 v73, v221, v222
	v_cvt_pk_bf16_f32 v74, v223, v224
	v_cvt_pk_bf16_f32 v75, v225, v226
	v_cvt_pk_bf16_f32 v76, v227, v228
	v_cvt_pk_bf16_f32 v77, v229, v230
	v_cvt_pk_bf16_f32 v78, v231, v232
	v_cvt_pk_bf16_f32 v79, v233, v195
	s_nop 0
	v_permlane32_swap_b32_e32 v64, v66
	v_permlane32_swap_b32_e32 v65, v67
	v_permlane32_swap_b32_e32 v68, v70
	v_permlane32_swap_b32_e32 v69, v71
	v_permlane32_swap_b32_e32 v72, v74
	v_permlane32_swap_b32_e32 v73, v75
	v_permlane32_swap_b32_e32 v76, v78
	v_permlane32_swap_b32_e32 v77, v79
	ds_read_b64_tr_b16 v[80:81], v215 offset:0
	ds_read_b64_tr_b16 v[82:83], v215 offset:0x800
	ds_read_b64_tr_b16 v[84:85], v215 offset:0x1000
	ds_read_b64_tr_b16 v[86:87], v215 offset:0x1800
	ds_read_b64_tr_b16 v[88:89], v215 offset:0x2000
	ds_read_b64_tr_b16 v[90:91], v215 offset:0x2800
	ds_read_b64_tr_b16 v[92:93], v215 offset:0x3000
	ds_read_b64_tr_b16 v[94:95], v215 offset:0x3800
	ds_read_b64_tr_b16 v[194:195], v215 offset:0x200
	ds_read_b64_tr_b16 v[196:197], v215 offset:0xa00
	ds_read_b64_tr_b16 v[222:223], v215 offset:0x1200
	ds_read_b64_tr_b16 v[224:225], v215 offset:0x1a00
	ds_read_b64_tr_b16 v[226:227], v215 offset:0x2200
	ds_read_b64_tr_b16 v[228:229], v215 offset:0x2a00
	ds_read_b64_tr_b16 v[230:231], v215 offset:0x3200
	ds_read_b64_tr_b16 v[232:233], v215 offset:0x3a00
	s_waitcnt lgkmcnt(8)
; #define SBAR() __builtin_amdgcn_sched_barrier(0)
; #define B_TILE(t, CUR) do { if ((t) + 1 < NT) { SWAIT(); SWRITE((CUR) ^ 1); if ((t) + 2 < NT) SLOAD((t) + 2); } S1(t, CUR); BARRIER(); \
;       S2(t, CUR); BARRIER(); } while (0)
; __device__ __forceinline__ void pv2(f32x16* o, int vb, bf16x8 pa0, bf16x8 pa1, bf16x8 pa2, bf16x8 pa3) {
;   VSet X, Y;
;   SBAR(); v_issue<0>(X, vb); v_issue<1>(Y, vb);
;   asm volatile("s_waitcnt lgkmcnt(8)" ::: "memory"); SBAR(); v_mma(o[0], X, pa0, pa1, pa2, pa3); SBAR();
;   v_issue<2>(X, vb);
;   asm volatile("s_waitcnt lgkmcnt(8)" ::: "memory"); SBAR(); v_mma(o[1], Y, pa0, pa1, pa2, pa3); SBAR();
;   v_issue<3>(Y, vb);
;   asm volatile("s_waitcnt lgkmcnt(8)" ::: "memory"); SBAR(); v_mma(o[2], X, pa0, pa1, pa2, pa3); SBAR();
;   asm volatile("s_waitcnt lgkmcnt(0)" ::: "memory"); SBAR(); v_mma(o[3], Y, pa0, pa1, pa2, pa3); SBAR();
; }
; __device__ __forceinline__ void attn_unit2(const bf16_t* __restrict__ Qb, const bf16_t* __restrict__ Kh, const bf16_t* __restrict__ Vh, ...
;     ...
;     for (int t = 0; t + 1 < NT; t += 2) { B_TILE(t, 0); B_TILE(t + 1, 1); }
	s_nop 0
	s_nop 0
	v_mfma_f32_32x32x16_bf16 v[0:15], v[64:67], v[80:83], v[0:15]
	v_mfma_f32_32x32x16_bf16 v[0:15], v[68:71], v[84:87], v[0:15]
	v_mfma_f32_32x32x16_bf16 v[0:15], v[72:75], v[88:91], v[0:15]
	v_mfma_f32_32x32x16_bf16 v[0:15], v[76:79], v[92:95], v[0:15]
	ds_read_b64_tr_b16 v[80:81], v215 offset:0x400
	ds_read_b64_tr_b16 v[82:83], v215 offset:0xc00
	ds_read_b64_tr_b16 v[84:85], v215 offset:0x1400
	ds_read_b64_tr_b16 v[86:87], v215 offset:0x1c00
	ds_read_b64_tr_b16 v[88:89], v215 offset:0x2400
	ds_read_b64_tr_b16 v[90:91], v215 offset:0x2c00
	ds_read_b64_tr_b16 v[92:93], v215 offset:0x3400
	ds_read_b64_tr_b16 v[94:95], v215 offset:0x3c00
	s_waitcnt lgkmcnt(8)
	s_nop 0
	v_mfma_f32_32x32x16_bf16 v[48:63], v[64:67], v[194:197], v[48:63]
	v_mfma_f32_32x32x16_bf16 v[48:63], v[68:71], v[222:225], v[48:63]
	v_mfma_f32_32x32x16_bf16 v[48:63], v[72:75], v[226:229], v[48:63]
	v_mfma_f32_32x32x16_bf16 v[48:63], v[76:79], v[230:233], v[48:63]
	ds_read_b64_tr_b16 v[194:195], v215 offset:0x600
	ds_read_b64_tr_b16 v[196:197], v215 offset:0xe00
	ds_read_b64_tr_b16 v[222:223], v215 offset:0x1600
	ds_read_b64_tr_b16 v[224:225], v215 offset:0x1e00
	ds_read_b64_tr_b16 v[226:227], v215 offset:0x2600
	ds_read_b64_tr_b16 v[228:229], v215 offset:0x2e00
	ds_read_b64_tr_b16 v[230:231], v215 offset:0x3600
	ds_read_b64_tr_b16 v[232:233], v215 offset:0x3e00
	s_waitcnt lgkmcnt(8)
	s_nop 0
	v_mfma_f32_32x32x16_bf16 v[32:47], v[64:67], v[80:83], v[32:47]
	v_mfma_f32_32x32x16_bf16 v[32:47], v[68:71], v[84:87], v[32:47]
	v_mfma_f32_32x32x16_bf16 v[32:47], v[72:75], v[88:91], v[32:47]
	v_mfma_f32_32x32x16_bf16 v[32:47], v[76:79], v[92:95], v[32:47]
	s_waitcnt lgkmcnt(0)
	s_nop 0
	v_mfma_f32_32x32x16_bf16 v[16:31], v[64:67], v[194:197], v[16:31]
	v_mfma_f32_32x32x16_bf16 v[16:31], v[68:71], v[222:225], v[16:31]
	v_mfma_f32_32x32x16_bf16 v[16:31], v[72:75], v[226:229], v[16:31]
	v_mfma_f32_32x32x16_bf16 v[16:31], v[76:79], v[230:233], v[16:31]
	s_add_i32 s0, s44, 2
	s_add_i32 s1, s44, 3
	s_add_i32 s42, s42, -2
	v_lshl_add_u64 v[190:191], v[190:191], 0, s[14:15]
	v_lshl_add_u64 v[192:193], v[192:193], 0, s[16:17]
	s_waitcnt lgkmcnt(0)
	s_barrier
	s_cmpk_gt_u32 s1, 0x100
	s_cbranch_scc1 .LBB0_453
	s_mov_b32 s44, s0
	s_branch .LBB0_441

; #define SBAR() __builtin_amdgcn_sched_barrier(0)
; __device__ __forceinline__ void finishSM(f32x16& p0, f32x16& p1, float alpha, float& l_reg, bf16x8& pa0, bf16x8& pa1, bf16x8& pa2, bf16x8& pa3) {
; #pragma unroll
;   for (int r = 0; r < 16; ++r) p1[r] = __builtin_amdgcn_exp2f(p1[r]);
;   float ps = 0;
; #pragma unroll
;   for (int r = 0; r < 16; ++r) ps += p0[r];
; #pragma unroll
;   for (int r = 0; r < 16; ++r) ps += p1[r];
;   { auto rr = __builtin_amdgcn_permlane32_swap(__float_as_uint(ps), __float_as_uint(ps), false, false);
;     ps = __uint_as_float(rr[0]) + __uint_as_float(rr[1]); }
;   l_reg = l_reg * alpha + ps;
;     ...
;   PK4(p0, 0, pa0); PK4(p0, 8, pa1); PK4(p1, 0, pa2); PK4(p1, 8, pa3);
; __device__ __forceinline__ void pv2(f32x16* o, int vb, bf16x8 pa0, bf16x8 pa1, bf16x8 pa2, bf16x8 pa3) {
;   VSet X, Y;
;   SBAR(); v_issue<0>(X, vb); v_issue<1>(Y, vb);
;   asm volatile("s_waitcnt lgkmcnt(8)" ::: "memory"); SBAR(); v_mma(o[0], X, pa0, pa1, pa2, pa3); SBAR();
;   v_issue<2>(X, vb);
.LBB0_469:
	v_cndmask_b32_e64 v178, v169, v178, s[8:9]
	v_mul_f32_e32 v169, 0xbdd53b94, v178
	v_fmamk_f32 v80, v80, 0x3dd53b94, v169
	v_fmamk_f32 v81, v81, 0x3dd53b94, v169
	v_fmamk_f32 v82, v82, 0x3dd53b94, v169
	v_fmamk_f32 v83, v83, 0x3dd53b94, v169
	v_fmamk_f32 v84, v84, 0x3dd53b94, v169
	v_fmamk_f32 v85, v85, 0x3dd53b94, v169
	v_fmamk_f32 v86, v86, 0x3dd53b94, v169
	v_fmamk_f32 v87, v87, 0x3dd53b94, v169
	v_fmamk_f32 v88, v88, 0x3dd53b94, v169
	v_fmamk_f32 v89, v89, 0x3dd53b94, v169
	v_fmamk_f32 v90, v90, 0x3dd53b94, v169
	v_fmamk_f32 v91, v91, 0x3dd53b94, v169
	v_fmamk_f32 v92, v92, 0x3dd53b94, v169
	v_fmamk_f32 v93, v93, 0x3dd53b94, v169
	v_fmamk_f32 v94, v94, 0x3dd53b94, v169
	v_fmamk_f32 v95, v95, 0x3dd53b94, v169
	v_fmamk_f32 v64, v64, 0x3dd53b94, v169
	v_fmamk_f32 v65, v65, 0x3dd53b94, v169
	v_fmamk_f32 v66, v66, 0x3dd53b94, v169
	v_fmamk_f32 v67, v67, 0x3dd53b94, v169
	v_fmamk_f32 v68, v68, 0x3dd53b94, v169
	v_fmamk_f32 v69, v69, 0x3dd53b94, v169
	v_fmamk_f32 v70, v70, 0x3dd53b94, v169
	v_fmamk_f32 v71, v71, 0x3dd53b94, v169
	v_fmamk_f32 v72, v72, 0x3dd53b94, v169
	v_fmamk_f32 v73, v73, 0x3dd53b94, v169
	v_fmamk_f32 v74, v74, 0x3dd53b94, v169
	v_fmamk_f32 v75, v75, 0x3dd53b94, v169
	v_fmamk_f32 v76, v76, 0x3dd53b94, v169
	v_fmamk_f32 v77, v77, 0x3dd53b94, v169
	v_fmamk_f32 v78, v78, 0x3dd53b94, v169
	v_fmac_f32_e32 v169, 0x3dd53b94, v79
	v_exp_f32_e32 v79, v80
	v_exp_f32_e32 v80, v81
	v_exp_f32_e32 v81, v82
	v_exp_f32_e32 v82, v83
	v_exp_f32_e32 v83, v84
	v_exp_f32_e32 v84, v85
	v_exp_f32_e32 v85, v86
	v_exp_f32_e32 v86, v87
	v_exp_f32_e32 v87, v88
	v_exp_f32_e32 v88, v89
	v_exp_f32_e32 v89, v90
	v_exp_f32_e32 v90, v91
	v_exp_f32_e32 v91, v92
	v_exp_f32_e32 v92, v93
	v_exp_f32_e32 v93, v94
	v_exp_f32_e32 v94, v95
	v_exp_f32_e32 v95, v64
	v_add_f32_e32 v64, 0, v79
	v_add_f32_e32 v64, v80, v64
	v_add_f32_e32 v64, v81, v64
	v_add_f32_e32 v64, v82, v64
	v_add_f32_e32 v64, v83, v64
	v_add_f32_e32 v64, v84, v64
	v_add_f32_e32 v64, v85, v64
	v_add_f32_e32 v64, v86, v64
	v_add_f32_e32 v64, v87, v64
	v_add_f32_e32 v64, v88, v64
	v_add_f32_e32 v64, v89, v64
	v_add_f32_e32 v64, v90, v64
	v_add_f32_e32 v64, v91, v64
	v_add_f32_e32 v170, v180, v181
	v_exp_f32_e32 v171, v65
	v_add_f32_e32 v64, v92, v64
	v_fmac_f32_e32 v170, v172, v179
	v_exp_f32_e32 v179, v66
	v_add_f32_e32 v64, v93, v64
	v_exp_f32_e32 v180, v67
	v_add_f32_e32 v64, v94, v64
	v_exp_f32_e32 v181, v68
	v_add_f32_e32 v64, v95, v64
	v_exp_f32_e32 v182, v69
	v_add_f32_e32 v64, v171, v64
	v_exp_f32_e32 v183, v70
	v_add_f32_e32 v64, v179, v64
	v_exp_f32_e32 v186, v71
	v_add_f32_e32 v64, v180, v64
	v_exp_f32_e32 v187, v72
	v_add_f32_e32 v64, v181, v64
	v_exp_f32_e32 v188, v73
	v_add_f32_e32 v64, v182, v64
	v_exp_f32_e32 v189, v74
	v_add_f32_e32 v64, v183, v64
	v_exp_f32_e32 v190, v75
	v_add_f32_e32 v64, v186, v64
	v_exp_f32_e32 v191, v76
	v_add_f32_e32 v64, v187, v64
	v_exp_f32_e32 v192, v77
	v_add_f32_e32 v64, v188, v64
	v_exp_f32_e32 v193, v78
	v_add_f32_e32 v64, v189, v64
	v_exp_f32_e32 v169, v169
	v_add_f32_e32 v64, v190, v64
	v_add_f32_e32 v64, v191, v64
	v_add_f32_e32 v64, v192, v64
	v_add_f32_e32 v64, v193, v64
	v_add_f32_e32 v64, v169, v64
	v_mov_b32_e32 v65, v64
	s_nop 1
	v_permlane32_swap_b32_e32 v64, v65
	v_add_f32_e32 v172, v64, v65
	v_fmac_f32_e32 v172, v170, v168
	v_cvt_pk_bf16_f32 v64, v79, v80
	v_cvt_pk_bf16_f32 v65, v81, v82
	v_cvt_pk_bf16_f32 v66, v83, v84
	v_cvt_pk_bf16_f32 v67, v85, v86
	v_cvt_pk_bf16_f32 v68, v87, v88
	v_cvt_pk_bf16_f32 v69, v89, v90
	v_cvt_pk_bf16_f32 v70, v91, v92
	v_cvt_pk_bf16_f32 v71, v93, v94
	v_cvt_pk_bf16_f32 v72, v95, v171
	v_cvt_pk_bf16_f32 v73, v179, v180
	v_cvt_pk_bf16_f32 v74, v181, v182
	v_cvt_pk_bf16_f32 v75, v183, v186
	v_cvt_pk_bf16_f32 v76, v187, v188
	v_cvt_pk_bf16_f32 v77, v189, v190
	v_cvt_pk_bf16_f32 v78, v191, v192
	v_cvt_pk_bf16_f32 v79, v193, v169
	s_nop 0
	v_permlane32_swap_b32_e32 v64, v66
	v_permlane32_swap_b32_e32 v65, v67
	v_permlane32_swap_b32_e32 v68, v70
	v_permlane32_swap_b32_e32 v69, v71
	v_permlane32_swap_b32_e32 v72, v74
	v_permlane32_swap_b32_e32 v73, v75
	v_permlane32_swap_b32_e32 v76, v78
	v_permlane32_swap_b32_e32 v77, v79
	ds_read_b64_tr_b16 v[80:81], v173 offset:0
	ds_read_b64_tr_b16 v[82:83], v173 offset:0x800
	ds_read_b64_tr_b16 v[84:85], v173 offset:0x1000
	ds_read_b64_tr_b16 v[86:87], v173 offset:0x1800
	ds_read_b64_tr_b16 v[88:89], v173 offset:0x2000
	ds_read_b64_tr_b16 v[90:91], v173 offset:0x2800
	ds_read_b64_tr_b16 v[92:93], v173 offset:0x3000
	ds_read_b64_tr_b16 v[94:95], v173 offset:0x3800
	ds_read_b64_tr_b16 v[168:169], v173 offset:0x200
	ds_read_b64_tr_b16 v[170:171], v173 offset:0xa00
	ds_read_b64_tr_b16 v[180:181], v173 offset:0x1200
	ds_read_b64_tr_b16 v[182:183], v173 offset:0x1a00
	ds_read_b64_tr_b16 v[186:187], v173 offset:0x2200
	ds_read_b64_tr_b16 v[188:189], v173 offset:0x2a00
	ds_read_b64_tr_b16 v[190:191], v173 offset:0x3200
	ds_read_b64_tr_b16 v[192:193], v173 offset:0x3a00
	s_waitcnt lgkmcnt(8)
; #define SBAR() __builtin_amdgcn_sched_barrier(0)
; #define SLOAD(t) do { const long r0_ = TROW(t); const bf16_t* vp_ = Vh + r0_ * LDV + vgo0; const bf16_t* kp_ = Kh + r0_ * LDKK + kgo0; \
;     vs0 = *reinterpret_cast<const bf16x8*>(vp_); vs1 = *reinterpret_cast<const bf16x8*>(vp_ + 64); \
;     ks0 = *reinterpret_cast<const bf16x8*>(kp_); ks1 = *reinterpret_cast<const bf16x8*>(kp_ + 64); ks2 = *reinterpret_cast<const bf16x8*>(kp_ + 128); } while (0)
; #define SLOAD(t) do { const long r0_ = TROW(t); const bf16_t* vp_ = Vh + r0_ * LDV + vgo0; const bf16_t* kp_ = Kh + r0_ * LDKK + kgo0; \
;     vs0 = *reinterpret_cast<const bf16x8*>(vp_); vs1 = *reinterpret_cast<const bf16x8*>(vp_ + 64); \
;     ks0 = *reinterpret_cast<const bf16x8*>(kp_); ks1 = *reinterpret_cast<const bf16x8*>(kp_ + 64); ks2 = *reinterpret_cast<const bf16x8*>(kp_ + 128); } while (0)
; #define A_TILE(t, CUR) do { S1(t, CUR); BARRIER(); \
;       if ((t) + 1 < NT) { SWAIT(); SWRITE((CUR) ^ 1); if ((t) + 2 < NT) SLOAD((t) + 2); } S2(t, CUR); BARRIER(); } while (0)
; __device__ __forceinline__ void pv2(f32x16* o, int vb, bf16x8 pa0, bf16x8 pa1, bf16x8 pa2, bf16x8 pa3) {
;   VSet X, Y;
;   SBAR(); v_issue<0>(X, vb); v_issue<1>(Y, vb);
;   asm volatile("s_waitcnt lgkmcnt(8)" ::: "memory"); SBAR(); v_mma(o[0], X, pa0, pa1, pa2, pa3); SBAR();
;   v_issue<2>(X, vb);
;   asm volatile("s_waitcnt lgkmcnt(8)" ::: "memory"); SBAR(); v_mma(o[1], Y, pa0, pa1, pa2, pa3); SBAR();
;   v_issue<3>(Y, vb);
;   asm volatile("s_waitcnt lgkmcnt(8)" ::: "memory"); SBAR(); v_mma(o[2], X, pa0, pa1, pa2, pa3); SBAR();
;   asm volatile("s_waitcnt lgkmcnt(0)" ::: "memory"); SBAR(); v_mma(o[3], Y, pa0, pa1, pa2, pa3); SBAR();
; }
; __device__ __forceinline__ void attn_unit2(const bf16_t* __restrict__ Qb, const bf16_t* __restrict__ Kh, const bf16_t* __restrict__ Vh, ...
;     ...
;     SLOAD(1);
;     for (int t = 0; t + 1 < NT; t += 2) { A_TILE(t, 0); A_TILE(t + 1, 1); }
	s_nop 0
	s_nop 0
	v_mfma_f32_32x32x16_bf16 v[0:15], v[64:67], v[80:83], v[0:15]
	v_mfma_f32_32x32x16_bf16 v[0:15], v[68:71], v[84:87], v[0:15]
	v_mfma_f32_32x32x16_bf16 v[0:15], v[72:75], v[88:91], v[0:15]
	v_mfma_f32_32x32x16_bf16 v[0:15], v[76:79], v[92:95], v[0:15]
	ds_read_b64_tr_b16 v[80:81], v173 offset:0x400
	ds_read_b64_tr_b16 v[82:83], v173 offset:0xc00
	ds_read_b64_tr_b16 v[84:85], v173 offset:0x1400
	ds_read_b64_tr_b16 v[86:87], v173 offset:0x1c00
	ds_read_b64_tr_b16 v[88:89], v173 offset:0x2400
	ds_read_b64_tr_b16 v[90:91], v173 offset:0x2c00
	ds_read_b64_tr_b16 v[92:93], v173 offset:0x3400
	ds_read_b64_tr_b16 v[94:95], v173 offset:0x3c00
	s_waitcnt lgkmcnt(8)
	s_nop 0
	v_mfma_f32_32x32x16_bf16 v[48:63], v[64:67], v[168:171], v[48:63]
	v_mfma_f32_32x32x16_bf16 v[48:63], v[68:71], v[180:183], v[48:63]
	v_mfma_f32_32x32x16_bf16 v[48:63], v[72:75], v[186:189], v[48:63]
	v_mfma_f32_32x32x16_bf16 v[48:63], v[76:79], v[190:193], v[48:63]
	ds_read_b64_tr_b16 v[168:169], v173 offset:0x600
	ds_read_b64_tr_b16 v[170:171], v173 offset:0xe00
	ds_read_b64_tr_b16 v[180:181], v173 offset:0x1600
	ds_read_b64_tr_b16 v[182:183], v173 offset:0x1e00
	ds_read_b64_tr_b16 v[186:187], v173 offset:0x2600
	ds_read_b64_tr_b16 v[188:189], v173 offset:0x2e00
	ds_read_b64_tr_b16 v[190:191], v173 offset:0x3600
	ds_read_b64_tr_b16 v[192:193], v173 offset:0x3e00
	s_waitcnt lgkmcnt(8)
	s_nop 0
	v_mfma_f32_32x32x16_bf16 v[32:47], v[64:67], v[80:83], v[32:47]
	v_mfma_f32_32x32x16_bf16 v[32:47], v[68:71], v[84:87], v[32:47]
	v_mfma_f32_32x32x16_bf16 v[32:47], v[72:75], v[88:91], v[32:47]
	v_mfma_f32_32x32x16_bf16 v[32:47], v[76:79], v[92:95], v[32:47]
	s_waitcnt lgkmcnt(0)
	s_nop 0
	v_mfma_f32_32x32x16_bf16 v[16:31], v[64:67], v[168:171], v[16:31]
	v_mfma_f32_32x32x16_bf16 v[16:31], v[68:71], v[180:183], v[16:31]
	v_mfma_f32_32x32x16_bf16 v[16:31], v[72:75], v[186:189], v[16:31]
	v_mfma_f32_32x32x16_bf16 v[16:31], v[76:79], v[190:193], v[16:31]
	s_add_i32 s0, s19, 2
	s_add_i32 s1, s19, 3
	s_add_i32 s42, s42, -2
	v_lshl_add_u64 v[164:165], v[164:165], 0, s[14:15]
	v_lshl_add_u64 v[166:167], v[166:167], 0, s[16:17]
	s_waitcnt lgkmcnt(0)
	s_barrier
	s_cmpk_gt_u32 s1, 0x100
	s_cbranch_scc1 .LBB0_471
	s_mov_b32 s19, s0
	s_branch .LBB0_459
